# scan compute loop rewritten by hand: state as row pairs, 607 vs 758 instr per 16-token chunk, vgpr 256
# baseline (speedup 1.0000x reference)
; __device__ __forceinline__ void scan_item(LAS unsigned char* lds, const ScanPtrs& P, bf16* YC, int item, unsigned* half_cnt, unsigned half_expect) {
;     ...
;         const int g = lane & 15, ra = 8 * wid + (lane >> 4);
;         f32x2 A01 = {0.f, 0.f}, A23 = {0.f, 0.f}, B01 = {0.f, 0.f}, B23 = {0.f, 0.f};
;         __builtin_amdgcn_s_setprio(3);
;         __syncthreads();
;         for (int c = 0; c < NCH; ++c) {
;             const LAS float* Bk = inb + (c & 1) * SC_INB + 4 * g;
;             const LAS float* Bv = inb + (c & 1) * SC_INB + 320 + ra;
;             LAS float* Y = ypb + (c & 1) * SC_YB + ra * 16 + g;
;             f32x4 cw, cm, cwr, ck, cr, nw, nm, nwr, nk, nr; float cva, cvb, nva, nvb;
;     ...
;             SC_RD(0, cw, cm, cwr, ck, cr, cva, cvb);
; #pragma unroll
;             for (int s = 0; s < SC_TC; ++s) {
;                 if (s + 1 < SC_TC) SC_RD(s + 1, nw, nm, nwr, nk, nr, nva, nvb);
;                 __builtin_amdgcn_sched_barrier(0);
;                 const f32x2 m01 = {cm[0], cm[1]}, m23 = {cm[2], cm[3]}, w01 = {cw[0], cw[1]}, w23 = {cw[2], cw[3]}, wr01 = {cwr[0], cwr[1]}, wr23 = {cwr[2], cwr[3]},
;                             k01 = {ck[0], ck[1]}, k23 = {ck[2], ck[3]}, r01 = {cr[0], cr[1]}, r23 = {cr[2], cr[3]};
;                 f32x2 qa = A01 * m01; qa = __builtin_elementwise_fma(A23, m23, qa);
;                 f32x2 qb = B01 * m01; qb = __builtin_elementwise_fma(B23, m23, qb);
;                 float da = qa[0] + qa[1], db = qb[0] + qb[1];
;                 const f32x2 vka01 = k01 * cva, vka23 = k23 * cva, vkb01 = k01 * cvb, vkb23 = k23 * cvb;
;                 da += dppf<0xB1>(da);  db += dppf<0xB1>(db);
;                 da += dppf<0x4E>(da);  db += dppf<0x4E>(db);
;                 da += dppf<0x141>(da); db += dppf<0x141>(db);
;                 da += dppf<0x140>(da); db += dppf<0x140>(db);
;                 const f32x2 sa2 = {da, da}, sb2 = {db, db};
;                 A01 = __builtin_elementwise_fma(A01, w01, __builtin_elementwise_fma(wr01, sa2, vka01)); A23 = __builtin_elementwise_fma(A23, w23, __builtin_elementwise_fma(wr23, sa2, vka23));
;                 B01 = __builtin_elementwise_fma(B01, w01, __builtin_elementwise_fma(wr01, sb2, vkb01)); B23 = __builtin_elementwise_fma(B23, w23, __builtin_elementwise_fma(wr23, sb2, vkb23));
;                 f32x2 ya = A01 * r01; ya = __builtin_elementwise_fma(A23, r23, ya);
.LBB0_726:
	v_readfirstlane_b32 s0, v152
	s_cmpk_lt_u32 s0, 0x100
	s_mov_b64 s[2:3], -1
	s_cbranch_scc0 .LBB0_730
	s_lshr_b32 s0, s0, 3
	v_and_or_b32 v6, s0, 24, v1
	s_setprio 3
	v_mov_b32_e32 v12, 0
	v_lshl_add_u32 v11, v6, 6, v50
	s_mov_b32 s0, 0
	v_mov_b32_e32 v13, v12
	v_mov_b32_e32 v14, v12
	v_mov_b32_e32 v15, v12
	v_mov_b32_e32 v16, v12
	v_mov_b32_e32 v17, v12
	v_mov_b32_e32 v18, v12
	v_mov_b32_e32 v19, v12
	s_and_b32 s2, s0, 1
	s_mul_i32 s3, s2, 0x5800
	s_addk_i32 s3, 0x100
	v_lshl_add_u32 v22, v6, 2, s3
	v_add_u32_e32 v21, s3, v3
	v_lshl_add_u32 v23, s2, 15, v11
	v_add_u32_e32 v20, 0xb000, v23
	s_waitcnt vmcnt(0)
	s_barrier
.LBB0_728:
	ds_read_b128 v[28:31], v21 offset:256
	ds_read_b128 v[36:39], v21 offset:768
	ds_read_b32 v44, v22 offset:1280
	ds_read_b32 v45, v22 offset:1296
	ds_read_b128 v[24:27], v21 offset:0
	ds_read_b128 v[32:35], v21 offset:512
	ds_read_b128 v[40:43], v21 offset:1024
	s_waitcnt lgkmcnt(6)
	v_pk_mul_f32 v[46:47], v[12:13], v[28:29] op_sel_hi:[1,0]
	ds_read_b128 v[68:71], v21 offset:1664
	v_pk_fma_f32 v[46:47], v[14:15], v[28:29], v[46:47] op_sel:[0,1,0]
	ds_read_b128 v[76:79], v21 offset:2176
	v_pk_fma_f32 v[46:47], v[16:17], v[30:31], v[46:47] op_sel_hi:[1,0,1]
	ds_read_b32 v84, v22 offset:2688
	v_pk_fma_f32 v[46:47], v[18:19], v[30:31], v[46:47] op_sel:[0,1,0]
	ds_read_b32 v85, v22 offset:2704
	s_waitcnt lgkmcnt(7)
	v_pk_mul_f32 v[248:249], v[36:37], v[44:45] op_sel_hi:[0,1]
	v_pk_mul_f32 v[250:251], v[36:37], v[44:45] op_sel:[1,0]
	v_add_f32_dpp v46, v46, v46 quad_perm:[1,0,3,2] row_mask:0xf bank_mask:0xf bound_ctrl:1
	v_add_f32_dpp v47, v47, v47 quad_perm:[1,0,3,2] row_mask:0xf bank_mask:0xf bound_ctrl:1
	ds_read_b128 v[64:67], v21 offset:1408
	v_add_f32_dpp v46, v46, v46 quad_perm:[2,3,0,1] row_mask:0xf bank_mask:0xf bound_ctrl:1
	v_add_f32_dpp v47, v47, v47 quad_perm:[2,3,0,1] row_mask:0xf bank_mask:0xf bound_ctrl:1
	ds_read_b128 v[72:75], v21 offset:1920
	v_add_f32_dpp v46, v46, v46 row_half_mirror row_mask:0xf bank_mask:0xf bound_ctrl:1
	v_add_f32_dpp v47, v47, v47 row_half_mirror row_mask:0xf bank_mask:0xf bound_ctrl:1
	v_pk_mul_f32 v[252:253], v[38:39], v[44:45] op_sel_hi:[0,1]
	v_add_f32_dpp v46, v46, v46 row_mirror row_mask:0xf bank_mask:0xf bound_ctrl:1
	v_add_f32_dpp v47, v47, v47 row_mirror row_mask:0xf bank_mask:0xf bound_ctrl:1
	v_pk_mul_f32 v[254:255], v[38:39], v[44:45] op_sel:[1,0]
	s_waitcnt lgkmcnt(7)
	v_pk_fma_f32 v[248:249], v[12:13], v[24:25], v[248:249] op_sel_hi:[1,0,1]
	v_pk_fma_f32 v[250:251], v[14:15], v[24:25], v[250:251] op_sel:[0,1,0]
	ds_read_b128 v[80:83], v21 offset:2432
	v_pk_fma_f32 v[252:253], v[16:17], v[26:27], v[252:253] op_sel_hi:[1,0,1]
	v_pk_fma_f32 v[254:255], v[18:19], v[26:27], v[254:255] op_sel:[0,1,0]
	v_pk_fma_f32 v[12:13], v[32:33], v[46:47], v[248:249] op_sel_hi:[0,1,1]
	v_pk_fma_f32 v[14:15], v[32:33], v[46:47], v[250:251] op_sel:[1,0,0]
	v_pk_fma_f32 v[16:17], v[34:35], v[46:47], v[252:253] op_sel_hi:[0,1,1]
	v_pk_fma_f32 v[18:19], v[34:35], v[46:47], v[254:255] op_sel:[1,0,0]
	s_waitcnt lgkmcnt(1)
	v_pk_mul_f32 v[46:47], v[12:13], v[68:69] op_sel_hi:[1,0]
	ds_read_b128 v[28:31], v21 offset:3072
	v_pk_mul_f32 v[48:49], v[12:13], v[40:41] op_sel_hi:[1,0]
	ds_read_b128 v[36:39], v21 offset:3584
	v_pk_fma_f32 v[46:47], v[14:15], v[68:69], v[46:47] op_sel:[0,1,0]
	ds_read_b32 v44, v22 offset:4096
	v_pk_fma_f32 v[48:49], v[14:15], v[40:41], v[48:49] op_sel:[0,1,0]
	ds_read_b32 v45, v22 offset:4112
	v_pk_fma_f32 v[46:47], v[16:17], v[70:71], v[46:47] op_sel_hi:[1,0,1]
	ds_read_b128 v[24:27], v21 offset:2816
	v_pk_fma_f32 v[48:49], v[16:17], v[42:43], v[48:49] op_sel_hi:[1,0,1]
	ds_read_b128 v[32:35], v21 offset:3328
	v_pk_fma_f32 v[46:47], v[18:19], v[70:71], v[46:47] op_sel:[0,1,0]
	v_pk_fma_f32 v[48:49], v[18:19], v[42:43], v[48:49] op_sel:[0,1,0]
	v_pk_mul_f32 v[248:249], v[76:77], v[84:85] op_sel_hi:[0,1]
	v_pk_mul_f32 v[250:251], v[76:77], v[84:85] op_sel:[1,0]
	v_add_f32_dpp v46, v46, v46 quad_perm:[1,0,3,2] row_mask:0xf bank_mask:0xf bound_ctrl:1
	v_add_f32_dpp v47, v47, v47 quad_perm:[1,0,3,2] row_mask:0xf bank_mask:0xf bound_ctrl:1
	ds_write2st64_b32 v20, v48, v49 offset0:0 offset1:1
	v_add_f32_dpp v46, v46, v46 quad_perm:[2,3,0,1] row_mask:0xf bank_mask:0xf bound_ctrl:1
	v_add_f32_dpp v47, v47, v47 quad_perm:[2,3,0,1] row_mask:0xf bank_mask:0xf bound_ctrl:1
	ds_read_b128 v[40:43], v21 offset:3840
	v_add_f32_dpp v46, v46, v46 row_half_mirror row_mask:0xf bank_mask:0xf bound_ctrl:1
	v_add_f32_dpp v47, v47, v47 row_half_mirror row_mask:0xf bank_mask:0xf bound_ctrl:1
	v_pk_mul_f32 v[252:253], v[78:79], v[84:85] op_sel_hi:[0,1]
	v_add_f32_dpp v46, v46, v46 row_mirror row_mask:0xf bank_mask:0xf bound_ctrl:1
	v_add_f32_dpp v47, v47, v47 row_mirror row_mask:0xf bank_mask:0xf bound_ctrl:1
	v_pk_mul_f32 v[254:255], v[78:79], v[84:85] op_sel:[1,0]
	v_pk_fma_f32 v[248:249], v[12:13], v[64:65], v[248:249] op_sel_hi:[1,0,1]
	v_pk_fma_f32 v[250:251], v[14:15], v[64:65], v[250:251] op_sel:[0,1,0]
	v_pk_fma_f32 v[252:253], v[16:17], v[66:67], v[252:253] op_sel_hi:[1,0,1]
	v_pk_fma_f32 v[254:255], v[18:19], v[66:67], v[254:255] op_sel:[0,1,0]
	v_pk_fma_f32 v[12:13], v[72:73], v[46:47], v[248:249] op_sel_hi:[0,1,1]
	v_pk_fma_f32 v[14:15], v[72:73], v[46:47], v[250:251] op_sel:[1,0,0]
	v_pk_fma_f32 v[16:17], v[74:75], v[46:47], v[252:253] op_sel_hi:[0,1,1]
	v_pk_fma_f32 v[18:19], v[74:75], v[46:47], v[254:255] op_sel:[1,0,0]
	s_waitcnt lgkmcnt(1)
; template <int CTRL> __device__ __forceinline__ float dppf(float x) { return __builtin_bit_cast(float, __builtin_amdgcn_update_dpp(0, __builtin_bit_cast(int, x), CTRL, 0xf, 0xf, true)); }
; __device__ __forceinline__ void scan_item(LAS unsigned char* lds, const ScanPtrs& P, bf16* YC, int item, unsigned* half_cnt, unsigned half_expect) {
;     ...
;             for (int s = 0; s < SC_TC; ++s) {
;                 if (s + 1 < SC_TC) SC_RD(s + 1, nw, nm, nwr, nk, nr, nva, nvb);
;                 __builtin_amdgcn_sched_barrier(0);
;                 const f32x2 m01 = {cm[0], cm[1]}, m23 = {cm[2], cm[3]}, w01 = {cw[0], cw[1]}, w23 = {cw[2], cw[3]}, wr01 = {cwr[0], cwr[1]}, wr23 = {cwr[2], cwr[3]},
;                             k01 = {ck[0], ck[1]}, k23 = {ck[2], ck[3]}, r01 = {cr[0], cr[1]}, r23 = {cr[2], cr[3]};
;                 f32x2 qa = A01 * m01; qa = __builtin_elementwise_fma(A23, m23, qa);
;                 f32x2 qb = B01 * m01; qb = __builtin_elementwise_fma(B23, m23, qb);
;                 float da = qa[0] + qa[1], db = qb[0] + qb[1];
;                 const f32x2 vka01 = k01 * cva, vka23 = k23 * cva, vkb01 = k01 * cvb, vkb23 = k23 * cvb;
;                 da += dppf<0xB1>(da);  db += dppf<0xB1>(db);
;                 da += dppf<0x4E>(da);  db += dppf<0x4E>(db);
;                 da += dppf<0x141>(da); db += dppf<0x141>(db);
;                 da += dppf<0x140>(da); db += dppf<0x140>(db);
;                 const f32x2 sa2 = {da, da}, sb2 = {db, db};
;                 A01 = __builtin_elementwise_fma(A01, w01, __builtin_elementwise_fma(wr01, sa2, vka01)); A23 = __builtin_elementwise_fma(A23, w23, __builtin_elementwise_fma(wr23, sa2, vka23));
;                 B01 = __builtin_elementwise_fma(B01, w01, __builtin_elementwise_fma(wr01, sb2, vkb01)); B23 = __builtin_elementwise_fma(B23, w23, __builtin_elementwise_fma(wr23, sb2, vkb23));
;                 f32x2 ya = A01 * r01; ya = __builtin_elementwise_fma(A23, r23, ya);
;                 f32x2 yb = B01 * r01; yb = __builtin_elementwise_fma(B23, r23, yb);
;                 Y[s * 512] = ya[0] + ya[1]; Y[s * 512 + 64] = yb[0] + yb[1];
;                 __builtin_amdgcn_sched_barrier(0);
;                 cw = nw; cm = nm; cwr = nwr; ck = nk; cr = nr; cva = nva; cvb = nvb;
;             }
	v_pk_mul_f32 v[46:47], v[12:13], v[28:29] op_sel_hi:[1,0]
	ds_read_b128 v[68:71], v21 offset:4480
	v_pk_mul_f32 v[48:49], v[12:13], v[80:81] op_sel_hi:[1,0]
	ds_read_b128 v[76:79], v21 offset:4992
	v_pk_fma_f32 v[46:47], v[14:15], v[28:29], v[46:47] op_sel:[0,1,0]
	ds_read_b32 v84, v22 offset:5504
	v_pk_fma_f32 v[48:49], v[14:15], v[80:81], v[48:49] op_sel:[0,1,0]
	ds_read_b32 v85, v22 offset:5520
	v_pk_fma_f32 v[46:47], v[16:17], v[30:31], v[46:47] op_sel_hi:[1,0,1]
	ds_read_b128 v[64:67], v21 offset:4224
	v_pk_fma_f32 v[48:49], v[16:17], v[82:83], v[48:49] op_sel_hi:[1,0,1]
	ds_read_b128 v[72:75], v21 offset:4736
	v_pk_fma_f32 v[46:47], v[18:19], v[30:31], v[46:47] op_sel:[0,1,0]
	v_pk_fma_f32 v[48:49], v[18:19], v[82:83], v[48:49] op_sel:[0,1,0]
	v_pk_mul_f32 v[248:249], v[36:37], v[44:45] op_sel_hi:[0,1]
	v_pk_mul_f32 v[250:251], v[36:37], v[44:45] op_sel:[1,0]
	v_add_f32_dpp v46, v46, v46 quad_perm:[1,0,3,2] row_mask:0xf bank_mask:0xf bound_ctrl:1
	v_add_f32_dpp v47, v47, v47 quad_perm:[1,0,3,2] row_mask:0xf bank_mask:0xf bound_ctrl:1
	ds_write2st64_b32 v20, v48, v49 offset0:8 offset1:9
	v_add_f32_dpp v46, v46, v46 quad_perm:[2,3,0,1] row_mask:0xf bank_mask:0xf bound_ctrl:1
	v_add_f32_dpp v47, v47, v47 quad_perm:[2,3,0,1] row_mask:0xf bank_mask:0xf bound_ctrl:1
	ds_read_b128 v[80:83], v21 offset:5248
	v_add_f32_dpp v46, v46, v46 row_half_mirror row_mask:0xf bank_mask:0xf bound_ctrl:1
	v_add_f32_dpp v47, v47, v47 row_half_mirror row_mask:0xf bank_mask:0xf bound_ctrl:1
	v_pk_mul_f32 v[252:253], v[38:39], v[44:45] op_sel_hi:[0,1]
	v_add_f32_dpp v46, v46, v46 row_mirror row_mask:0xf bank_mask:0xf bound_ctrl:1
	v_add_f32_dpp v47, v47, v47 row_mirror row_mask:0xf bank_mask:0xf bound_ctrl:1
	v_pk_mul_f32 v[254:255], v[38:39], v[44:45] op_sel:[1,0]
	v_pk_fma_f32 v[248:249], v[12:13], v[24:25], v[248:249] op_sel_hi:[1,0,1]
	v_pk_fma_f32 v[250:251], v[14:15], v[24:25], v[250:251] op_sel:[0,1,0]
	v_pk_fma_f32 v[252:253], v[16:17], v[26:27], v[252:253] op_sel_hi:[1,0,1]
	v_pk_fma_f32 v[254:255], v[18:19], v[26:27], v[254:255] op_sel:[0,1,0]
	v_pk_fma_f32 v[12:13], v[32:33], v[46:47], v[248:249] op_sel_hi:[0,1,1]
	v_pk_fma_f32 v[14:15], v[32:33], v[46:47], v[250:251] op_sel:[1,0,0]
	v_pk_fma_f32 v[16:17], v[34:35], v[46:47], v[252:253] op_sel_hi:[0,1,1]
	v_pk_fma_f32 v[18:19], v[34:35], v[46:47], v[254:255] op_sel:[1,0,0]
	s_waitcnt lgkmcnt(1)
	v_pk_mul_f32 v[46:47], v[12:13], v[68:69] op_sel_hi:[1,0]
	ds_read_b128 v[28:31], v21 offset:5888
	v_pk_mul_f32 v[48:49], v[12:13], v[40:41] op_sel_hi:[1,0]
	ds_read_b128 v[36:39], v21 offset:6400
	v_pk_fma_f32 v[46:47], v[14:15], v[68:69], v[46:47] op_sel:[0,1,0]
	ds_read_b32 v44, v22 offset:6912
	v_pk_fma_f32 v[48:49], v[14:15], v[40:41], v[48:49] op_sel:[0,1,0]
	ds_read_b32 v45, v22 offset:6928
	v_pk_fma_f32 v[46:47], v[16:17], v[70:71], v[46:47] op_sel_hi:[1,0,1]
	ds_read_b128 v[24:27], v21 offset:5632
	v_pk_fma_f32 v[48:49], v[16:17], v[42:43], v[48:49] op_sel_hi:[1,0,1]
	ds_read_b128 v[32:35], v21 offset:6144
	v_pk_fma_f32 v[46:47], v[18:19], v[70:71], v[46:47] op_sel:[0,1,0]
	v_pk_fma_f32 v[48:49], v[18:19], v[42:43], v[48:49] op_sel:[0,1,0]
	v_pk_mul_f32 v[248:249], v[76:77], v[84:85] op_sel_hi:[0,1]
	v_pk_mul_f32 v[250:251], v[76:77], v[84:85] op_sel:[1,0]
	v_add_f32_dpp v46, v46, v46 quad_perm:[1,0,3,2] row_mask:0xf bank_mask:0xf bound_ctrl:1
	v_add_f32_dpp v47, v47, v47 quad_perm:[1,0,3,2] row_mask:0xf bank_mask:0xf bound_ctrl:1
	ds_write2st64_b32 v20, v48, v49 offset0:16 offset1:17
	v_add_f32_dpp v46, v46, v46 quad_perm:[2,3,0,1] row_mask:0xf bank_mask:0xf bound_ctrl:1
	v_add_f32_dpp v47, v47, v47 quad_perm:[2,3,0,1] row_mask:0xf bank_mask:0xf bound_ctrl:1
	ds_read_b128 v[40:43], v21 offset:6656
	v_add_f32_dpp v46, v46, v46 row_half_mirror row_mask:0xf bank_mask:0xf bound_ctrl:1
	v_add_f32_dpp v47, v47, v47 row_half_mirror row_mask:0xf bank_mask:0xf bound_ctrl:1
	v_pk_mul_f32 v[252:253], v[78:79], v[84:85] op_sel_hi:[0,1]
	v_add_f32_dpp v46, v46, v46 row_mirror row_mask:0xf bank_mask:0xf bound_ctrl:1
	v_add_f32_dpp v47, v47, v47 row_mirror row_mask:0xf bank_mask:0xf bound_ctrl:1
	v_pk_mul_f32 v[254:255], v[78:79], v[84:85] op_sel:[1,0]
	v_pk_fma_f32 v[248:249], v[12:13], v[64:65], v[248:249] op_sel_hi:[1,0,1]
	v_pk_fma_f32 v[250:251], v[14:15], v[64:65], v[250:251] op_sel:[0,1,0]
	v_pk_fma_f32 v[252:253], v[16:17], v[66:67], v[252:253] op_sel_hi:[1,0,1]
	v_pk_fma_f32 v[254:255], v[18:19], v[66:67], v[254:255] op_sel:[0,1,0]
	v_pk_fma_f32 v[12:13], v[72:73], v[46:47], v[248:249] op_sel_hi:[0,1,1]
	v_pk_fma_f32 v[14:15], v[72:73], v[46:47], v[250:251] op_sel:[1,0,0]
	v_pk_fma_f32 v[16:17], v[74:75], v[46:47], v[252:253] op_sel_hi:[0,1,1]
	v_pk_fma_f32 v[18:19], v[74:75], v[46:47], v[254:255] op_sel:[1,0,0]
	s_waitcnt lgkmcnt(1)
; template <int CTRL> __device__ __forceinline__ float dppf(float x) { return __builtin_bit_cast(float, __builtin_amdgcn_update_dpp(0, __builtin_bit_cast(int, x), CTRL, 0xf, 0xf, true)); }
; __device__ __forceinline__ void scan_item(LAS unsigned char* lds, const ScanPtrs& P, bf16* YC, int item, unsigned* half_cnt, unsigned half_expect) {
;     ...
;             for (int s = 0; s < SC_TC; ++s) {
;                 if (s + 1 < SC_TC) SC_RD(s + 1, nw, nm, nwr, nk, nr, nva, nvb);
;                 __builtin_amdgcn_sched_barrier(0);
;                 const f32x2 m01 = {cm[0], cm[1]}, m23 = {cm[2], cm[3]}, w01 = {cw[0], cw[1]}, w23 = {cw[2], cw[3]}, wr01 = {cwr[0], cwr[1]}, wr23 = {cwr[2], cwr[3]},
;                             k01 = {ck[0], ck[1]}, k23 = {ck[2], ck[3]}, r01 = {cr[0], cr[1]}, r23 = {cr[2], cr[3]};
;                 f32x2 qa = A01 * m01; qa = __builtin_elementwise_fma(A23, m23, qa);
;                 f32x2 qb = B01 * m01; qb = __builtin_elementwise_fma(B23, m23, qb);
;                 float da = qa[0] + qa[1], db = qb[0] + qb[1];
;                 const f32x2 vka01 = k01 * cva, vka23 = k23 * cva, vkb01 = k01 * cvb, vkb23 = k23 * cvb;
;                 da += dppf<0xB1>(da);  db += dppf<0xB1>(db);
;                 da += dppf<0x4E>(da);  db += dppf<0x4E>(db);
;                 da += dppf<0x141>(da); db += dppf<0x141>(db);
;                 da += dppf<0x140>(da); db += dppf<0x140>(db);
;                 const f32x2 sa2 = {da, da}, sb2 = {db, db};
;                 A01 = __builtin_elementwise_fma(A01, w01, __builtin_elementwise_fma(wr01, sa2, vka01)); A23 = __builtin_elementwise_fma(A23, w23, __builtin_elementwise_fma(wr23, sa2, vka23));
;                 B01 = __builtin_elementwise_fma(B01, w01, __builtin_elementwise_fma(wr01, sb2, vkb01)); B23 = __builtin_elementwise_fma(B23, w23, __builtin_elementwise_fma(wr23, sb2, vkb23));
;                 f32x2 ya = A01 * r01; ya = __builtin_elementwise_fma(A23, r23, ya);
;                 f32x2 yb = B01 * r01; yb = __builtin_elementwise_fma(B23, r23, yb);
;                 Y[s * 512] = ya[0] + ya[1]; Y[s * 512 + 64] = yb[0] + yb[1];
;                 __builtin_amdgcn_sched_barrier(0);
;                 cw = nw; cm = nm; cwr = nwr; ck = nk; cr = nr; cva = nva; cvb = nvb;
;             }
	v_pk_mul_f32 v[46:47], v[12:13], v[28:29] op_sel_hi:[1,0]
	ds_read_b128 v[68:71], v21 offset:7296
	v_pk_mul_f32 v[48:49], v[12:13], v[80:81] op_sel_hi:[1,0]
	ds_read_b128 v[76:79], v21 offset:7808
	v_pk_fma_f32 v[46:47], v[14:15], v[28:29], v[46:47] op_sel:[0,1,0]
	ds_read_b32 v84, v22 offset:8320
	v_pk_fma_f32 v[48:49], v[14:15], v[80:81], v[48:49] op_sel:[0,1,0]
	ds_read_b32 v85, v22 offset:8336
	v_pk_fma_f32 v[46:47], v[16:17], v[30:31], v[46:47] op_sel_hi:[1,0,1]
	ds_read_b128 v[64:67], v21 offset:7040
	v_pk_fma_f32 v[48:49], v[16:17], v[82:83], v[48:49] op_sel_hi:[1,0,1]
	ds_read_b128 v[72:75], v21 offset:7552
	v_pk_fma_f32 v[46:47], v[18:19], v[30:31], v[46:47] op_sel:[0,1,0]
	v_pk_fma_f32 v[48:49], v[18:19], v[82:83], v[48:49] op_sel:[0,1,0]
	v_pk_mul_f32 v[248:249], v[36:37], v[44:45] op_sel_hi:[0,1]
	v_pk_mul_f32 v[250:251], v[36:37], v[44:45] op_sel:[1,0]
	v_add_f32_dpp v46, v46, v46 quad_perm:[1,0,3,2] row_mask:0xf bank_mask:0xf bound_ctrl:1
	v_add_f32_dpp v47, v47, v47 quad_perm:[1,0,3,2] row_mask:0xf bank_mask:0xf bound_ctrl:1
	ds_write2st64_b32 v20, v48, v49 offset0:24 offset1:25
	v_add_f32_dpp v46, v46, v46 quad_perm:[2,3,0,1] row_mask:0xf bank_mask:0xf bound_ctrl:1
	v_add_f32_dpp v47, v47, v47 quad_perm:[2,3,0,1] row_mask:0xf bank_mask:0xf bound_ctrl:1
	ds_read_b128 v[80:83], v21 offset:8064
	v_add_f32_dpp v46, v46, v46 row_half_mirror row_mask:0xf bank_mask:0xf bound_ctrl:1
	v_add_f32_dpp v47, v47, v47 row_half_mirror row_mask:0xf bank_mask:0xf bound_ctrl:1
	v_pk_mul_f32 v[252:253], v[38:39], v[44:45] op_sel_hi:[0,1]
	v_add_f32_dpp v46, v46, v46 row_mirror row_mask:0xf bank_mask:0xf bound_ctrl:1
	v_add_f32_dpp v47, v47, v47 row_mirror row_mask:0xf bank_mask:0xf bound_ctrl:1
	v_pk_mul_f32 v[254:255], v[38:39], v[44:45] op_sel:[1,0]
	v_pk_fma_f32 v[248:249], v[12:13], v[24:25], v[248:249] op_sel_hi:[1,0,1]
	v_pk_fma_f32 v[250:251], v[14:15], v[24:25], v[250:251] op_sel:[0,1,0]
	v_pk_fma_f32 v[252:253], v[16:17], v[26:27], v[252:253] op_sel_hi:[1,0,1]
	v_pk_fma_f32 v[254:255], v[18:19], v[26:27], v[254:255] op_sel:[0,1,0]
	v_pk_fma_f32 v[12:13], v[32:33], v[46:47], v[248:249] op_sel_hi:[0,1,1]
	v_pk_fma_f32 v[14:15], v[32:33], v[46:47], v[250:251] op_sel:[1,0,0]
	v_pk_fma_f32 v[16:17], v[34:35], v[46:47], v[252:253] op_sel_hi:[0,1,1]
	v_pk_fma_f32 v[18:19], v[34:35], v[46:47], v[254:255] op_sel:[1,0,0]
	s_waitcnt lgkmcnt(1)
	v_pk_mul_f32 v[46:47], v[12:13], v[68:69] op_sel_hi:[1,0]
	ds_read_b128 v[28:31], v21 offset:8704
	v_pk_mul_f32 v[48:49], v[12:13], v[40:41] op_sel_hi:[1,0]
	ds_read_b128 v[36:39], v21 offset:9216
	v_pk_fma_f32 v[46:47], v[14:15], v[68:69], v[46:47] op_sel:[0,1,0]
	ds_read_b32 v44, v22 offset:9728
	v_pk_fma_f32 v[48:49], v[14:15], v[40:41], v[48:49] op_sel:[0,1,0]
	ds_read_b32 v45, v22 offset:9744
	v_pk_fma_f32 v[46:47], v[16:17], v[70:71], v[46:47] op_sel_hi:[1,0,1]
	ds_read_b128 v[24:27], v21 offset:8448
	v_pk_fma_f32 v[48:49], v[16:17], v[42:43], v[48:49] op_sel_hi:[1,0,1]
	ds_read_b128 v[32:35], v21 offset:8960
	v_pk_fma_f32 v[46:47], v[18:19], v[70:71], v[46:47] op_sel:[0,1,0]
	v_pk_fma_f32 v[48:49], v[18:19], v[42:43], v[48:49] op_sel:[0,1,0]
	v_pk_mul_f32 v[248:249], v[76:77], v[84:85] op_sel_hi:[0,1]
	v_pk_mul_f32 v[250:251], v[76:77], v[84:85] op_sel:[1,0]
	v_add_f32_dpp v46, v46, v46 quad_perm:[1,0,3,2] row_mask:0xf bank_mask:0xf bound_ctrl:1
	v_add_f32_dpp v47, v47, v47 quad_perm:[1,0,3,2] row_mask:0xf bank_mask:0xf bound_ctrl:1
	ds_write2st64_b32 v20, v48, v49 offset0:32 offset1:33
	v_add_f32_dpp v46, v46, v46 quad_perm:[2,3,0,1] row_mask:0xf bank_mask:0xf bound_ctrl:1
	v_add_f32_dpp v47, v47, v47 quad_perm:[2,3,0,1] row_mask:0xf bank_mask:0xf bound_ctrl:1
	ds_read_b128 v[40:43], v21 offset:9472
	v_add_f32_dpp v46, v46, v46 row_half_mirror row_mask:0xf bank_mask:0xf bound_ctrl:1
	v_add_f32_dpp v47, v47, v47 row_half_mirror row_mask:0xf bank_mask:0xf bound_ctrl:1
	v_pk_mul_f32 v[252:253], v[78:79], v[84:85] op_sel_hi:[0,1]
	v_add_f32_dpp v46, v46, v46 row_mirror row_mask:0xf bank_mask:0xf bound_ctrl:1
	v_add_f32_dpp v47, v47, v47 row_mirror row_mask:0xf bank_mask:0xf bound_ctrl:1
	v_pk_mul_f32 v[254:255], v[78:79], v[84:85] op_sel:[1,0]
	v_pk_fma_f32 v[248:249], v[12:13], v[64:65], v[248:249] op_sel_hi:[1,0,1]
	v_pk_fma_f32 v[250:251], v[14:15], v[64:65], v[250:251] op_sel:[0,1,0]
	v_pk_fma_f32 v[252:253], v[16:17], v[66:67], v[252:253] op_sel_hi:[1,0,1]
	v_pk_fma_f32 v[254:255], v[18:19], v[66:67], v[254:255] op_sel:[0,1,0]
	v_pk_fma_f32 v[12:13], v[72:73], v[46:47], v[248:249] op_sel_hi:[0,1,1]
	v_pk_fma_f32 v[14:15], v[72:73], v[46:47], v[250:251] op_sel:[1,0,0]
	v_pk_fma_f32 v[16:17], v[74:75], v[46:47], v[252:253] op_sel_hi:[0,1,1]
	v_pk_fma_f32 v[18:19], v[74:75], v[46:47], v[254:255] op_sel:[1,0,0]
	s_waitcnt lgkmcnt(1)
; template <int CTRL> __device__ __forceinline__ float dppf(float x) { return __builtin_bit_cast(float, __builtin_amdgcn_update_dpp(0, __builtin_bit_cast(int, x), CTRL, 0xf, 0xf, true)); }
; __device__ __forceinline__ void scan_item(LAS unsigned char* lds, const ScanPtrs& P, bf16* YC, int item, unsigned* half_cnt, unsigned half_expect) {
;     ...
;             for (int s = 0; s < SC_TC; ++s) {
;                 if (s + 1 < SC_TC) SC_RD(s + 1, nw, nm, nwr, nk, nr, nva, nvb);
;                 __builtin_amdgcn_sched_barrier(0);
;                 const f32x2 m01 = {cm[0], cm[1]}, m23 = {cm[2], cm[3]}, w01 = {cw[0], cw[1]}, w23 = {cw[2], cw[3]}, wr01 = {cwr[0], cwr[1]}, wr23 = {cwr[2], cwr[3]},
;                             k01 = {ck[0], ck[1]}, k23 = {ck[2], ck[3]}, r01 = {cr[0], cr[1]}, r23 = {cr[2], cr[3]};
;                 f32x2 qa = A01 * m01; qa = __builtin_elementwise_fma(A23, m23, qa);
;                 f32x2 qb = B01 * m01; qb = __builtin_elementwise_fma(B23, m23, qb);
;                 float da = qa[0] + qa[1], db = qb[0] + qb[1];
;                 const f32x2 vka01 = k01 * cva, vka23 = k23 * cva, vkb01 = k01 * cvb, vkb23 = k23 * cvb;
;                 da += dppf<0xB1>(da);  db += dppf<0xB1>(db);
;                 da += dppf<0x4E>(da);  db += dppf<0x4E>(db);
;                 da += dppf<0x141>(da); db += dppf<0x141>(db);
;                 da += dppf<0x140>(da); db += dppf<0x140>(db);
;                 const f32x2 sa2 = {da, da}, sb2 = {db, db};
;                 A01 = __builtin_elementwise_fma(A01, w01, __builtin_elementwise_fma(wr01, sa2, vka01)); A23 = __builtin_elementwise_fma(A23, w23, __builtin_elementwise_fma(wr23, sa2, vka23));
;                 B01 = __builtin_elementwise_fma(B01, w01, __builtin_elementwise_fma(wr01, sb2, vkb01)); B23 = __builtin_elementwise_fma(B23, w23, __builtin_elementwise_fma(wr23, sb2, vkb23));
;                 f32x2 ya = A01 * r01; ya = __builtin_elementwise_fma(A23, r23, ya);
;                 f32x2 yb = B01 * r01; yb = __builtin_elementwise_fma(B23, r23, yb);
;                 Y[s * 512] = ya[0] + ya[1]; Y[s * 512 + 64] = yb[0] + yb[1];
;                 __builtin_amdgcn_sched_barrier(0);
;                 cw = nw; cm = nm; cwr = nwr; ck = nk; cr = nr; cva = nva; cvb = nvb;
;             }
	v_pk_mul_f32 v[46:47], v[12:13], v[28:29] op_sel_hi:[1,0]
	ds_read_b128 v[68:71], v21 offset:10112
	v_pk_mul_f32 v[48:49], v[12:13], v[80:81] op_sel_hi:[1,0]
	ds_read_b128 v[76:79], v21 offset:10624
	v_pk_fma_f32 v[46:47], v[14:15], v[28:29], v[46:47] op_sel:[0,1,0]
	ds_read_b32 v84, v22 offset:11136
	v_pk_fma_f32 v[48:49], v[14:15], v[80:81], v[48:49] op_sel:[0,1,0]
	ds_read_b32 v85, v22 offset:11152
	v_pk_fma_f32 v[46:47], v[16:17], v[30:31], v[46:47] op_sel_hi:[1,0,1]
	ds_read_b128 v[64:67], v21 offset:9856
	v_pk_fma_f32 v[48:49], v[16:17], v[82:83], v[48:49] op_sel_hi:[1,0,1]
	ds_read_b128 v[72:75], v21 offset:10368
	v_pk_fma_f32 v[46:47], v[18:19], v[30:31], v[46:47] op_sel:[0,1,0]
	v_pk_fma_f32 v[48:49], v[18:19], v[82:83], v[48:49] op_sel:[0,1,0]
	v_pk_mul_f32 v[248:249], v[36:37], v[44:45] op_sel_hi:[0,1]
	v_pk_mul_f32 v[250:251], v[36:37], v[44:45] op_sel:[1,0]
	v_add_f32_dpp v46, v46, v46 quad_perm:[1,0,3,2] row_mask:0xf bank_mask:0xf bound_ctrl:1
	v_add_f32_dpp v47, v47, v47 quad_perm:[1,0,3,2] row_mask:0xf bank_mask:0xf bound_ctrl:1
	ds_write2st64_b32 v20, v48, v49 offset0:40 offset1:41
	v_add_f32_dpp v46, v46, v46 quad_perm:[2,3,0,1] row_mask:0xf bank_mask:0xf bound_ctrl:1
	v_add_f32_dpp v47, v47, v47 quad_perm:[2,3,0,1] row_mask:0xf bank_mask:0xf bound_ctrl:1
	ds_read_b128 v[80:83], v21 offset:10880
	v_add_f32_dpp v46, v46, v46 row_half_mirror row_mask:0xf bank_mask:0xf bound_ctrl:1
	v_add_f32_dpp v47, v47, v47 row_half_mirror row_mask:0xf bank_mask:0xf bound_ctrl:1
	v_pk_mul_f32 v[252:253], v[38:39], v[44:45] op_sel_hi:[0,1]
	v_add_f32_dpp v46, v46, v46 row_mirror row_mask:0xf bank_mask:0xf bound_ctrl:1
	v_add_f32_dpp v47, v47, v47 row_mirror row_mask:0xf bank_mask:0xf bound_ctrl:1
	v_pk_mul_f32 v[254:255], v[38:39], v[44:45] op_sel:[1,0]
	v_pk_fma_f32 v[248:249], v[12:13], v[24:25], v[248:249] op_sel_hi:[1,0,1]
	v_pk_fma_f32 v[250:251], v[14:15], v[24:25], v[250:251] op_sel:[0,1,0]
	v_pk_fma_f32 v[252:253], v[16:17], v[26:27], v[252:253] op_sel_hi:[1,0,1]
	v_pk_fma_f32 v[254:255], v[18:19], v[26:27], v[254:255] op_sel:[0,1,0]
	v_pk_fma_f32 v[12:13], v[32:33], v[46:47], v[248:249] op_sel_hi:[0,1,1]
	v_pk_fma_f32 v[14:15], v[32:33], v[46:47], v[250:251] op_sel:[1,0,0]
	v_pk_fma_f32 v[16:17], v[34:35], v[46:47], v[252:253] op_sel_hi:[0,1,1]
	v_pk_fma_f32 v[18:19], v[34:35], v[46:47], v[254:255] op_sel:[1,0,0]
	s_waitcnt lgkmcnt(1)
	v_pk_mul_f32 v[46:47], v[12:13], v[68:69] op_sel_hi:[1,0]
	ds_read_b128 v[28:31], v21 offset:11520
	v_pk_mul_f32 v[48:49], v[12:13], v[40:41] op_sel_hi:[1,0]
	ds_read_b128 v[36:39], v21 offset:12032
	v_pk_fma_f32 v[46:47], v[14:15], v[68:69], v[46:47] op_sel:[0,1,0]
	ds_read_b32 v44, v22 offset:12544
	v_pk_fma_f32 v[48:49], v[14:15], v[40:41], v[48:49] op_sel:[0,1,0]
	ds_read_b32 v45, v22 offset:12560
	v_pk_fma_f32 v[46:47], v[16:17], v[70:71], v[46:47] op_sel_hi:[1,0,1]
	ds_read_b128 v[24:27], v21 offset:11264
	v_pk_fma_f32 v[48:49], v[16:17], v[42:43], v[48:49] op_sel_hi:[1,0,1]
	ds_read_b128 v[32:35], v21 offset:11776
	v_pk_fma_f32 v[46:47], v[18:19], v[70:71], v[46:47] op_sel:[0,1,0]
	v_pk_fma_f32 v[48:49], v[18:19], v[42:43], v[48:49] op_sel:[0,1,0]
	v_pk_mul_f32 v[248:249], v[76:77], v[84:85] op_sel_hi:[0,1]
	v_pk_mul_f32 v[250:251], v[76:77], v[84:85] op_sel:[1,0]
	v_add_f32_dpp v46, v46, v46 quad_perm:[1,0,3,2] row_mask:0xf bank_mask:0xf bound_ctrl:1
	v_add_f32_dpp v47, v47, v47 quad_perm:[1,0,3,2] row_mask:0xf bank_mask:0xf bound_ctrl:1
	ds_write2st64_b32 v20, v48, v49 offset0:48 offset1:49
	v_add_f32_dpp v46, v46, v46 quad_perm:[2,3,0,1] row_mask:0xf bank_mask:0xf bound_ctrl:1
	v_add_f32_dpp v47, v47, v47 quad_perm:[2,3,0,1] row_mask:0xf bank_mask:0xf bound_ctrl:1
	ds_read_b128 v[40:43], v21 offset:12288
	v_add_f32_dpp v46, v46, v46 row_half_mirror row_mask:0xf bank_mask:0xf bound_ctrl:1
	v_add_f32_dpp v47, v47, v47 row_half_mirror row_mask:0xf bank_mask:0xf bound_ctrl:1
	v_pk_mul_f32 v[252:253], v[78:79], v[84:85] op_sel_hi:[0,1]
	v_add_f32_dpp v46, v46, v46 row_mirror row_mask:0xf bank_mask:0xf bound_ctrl:1
	v_add_f32_dpp v47, v47, v47 row_mirror row_mask:0xf bank_mask:0xf bound_ctrl:1
	v_pk_mul_f32 v[254:255], v[78:79], v[84:85] op_sel:[1,0]
	v_pk_fma_f32 v[248:249], v[12:13], v[64:65], v[248:249] op_sel_hi:[1,0,1]
	v_pk_fma_f32 v[250:251], v[14:15], v[64:65], v[250:251] op_sel:[0,1,0]
	v_pk_fma_f32 v[252:253], v[16:17], v[66:67], v[252:253] op_sel_hi:[1,0,1]
	v_pk_fma_f32 v[254:255], v[18:19], v[66:67], v[254:255] op_sel:[0,1,0]
	v_pk_fma_f32 v[12:13], v[72:73], v[46:47], v[248:249] op_sel_hi:[0,1,1]
	v_pk_fma_f32 v[14:15], v[72:73], v[46:47], v[250:251] op_sel:[1,0,0]
	v_pk_fma_f32 v[16:17], v[74:75], v[46:47], v[252:253] op_sel_hi:[0,1,1]
	v_pk_fma_f32 v[18:19], v[74:75], v[46:47], v[254:255] op_sel:[1,0,0]
	s_waitcnt lgkmcnt(1)
; template <int CTRL> __device__ __forceinline__ float dppf(float x) { return __builtin_bit_cast(float, __builtin_amdgcn_update_dpp(0, __builtin_bit_cast(int, x), CTRL, 0xf, 0xf, true)); }
; __device__ __forceinline__ void scan_item(LAS unsigned char* lds, const ScanPtrs& P, bf16* YC, int item, unsigned* half_cnt, unsigned half_expect) {
;     ...
;             for (int s = 0; s < SC_TC; ++s) {
;                 if (s + 1 < SC_TC) SC_RD(s + 1, nw, nm, nwr, nk, nr, nva, nvb);
;                 __builtin_amdgcn_sched_barrier(0);
;                 const f32x2 m01 = {cm[0], cm[1]}, m23 = {cm[2], cm[3]}, w01 = {cw[0], cw[1]}, w23 = {cw[2], cw[3]}, wr01 = {cwr[0], cwr[1]}, wr23 = {cwr[2], cwr[3]},
;                             k01 = {ck[0], ck[1]}, k23 = {ck[2], ck[3]}, r01 = {cr[0], cr[1]}, r23 = {cr[2], cr[3]};
;                 f32x2 qa = A01 * m01; qa = __builtin_elementwise_fma(A23, m23, qa);
;                 f32x2 qb = B01 * m01; qb = __builtin_elementwise_fma(B23, m23, qb);
;                 float da = qa[0] + qa[1], db = qb[0] + qb[1];
;                 const f32x2 vka01 = k01 * cva, vka23 = k23 * cva, vkb01 = k01 * cvb, vkb23 = k23 * cvb;
;                 da += dppf<0xB1>(da);  db += dppf<0xB1>(db);
;                 da += dppf<0x4E>(da);  db += dppf<0x4E>(db);
;                 da += dppf<0x141>(da); db += dppf<0x141>(db);
;                 da += dppf<0x140>(da); db += dppf<0x140>(db);
;                 const f32x2 sa2 = {da, da}, sb2 = {db, db};
;                 A01 = __builtin_elementwise_fma(A01, w01, __builtin_elementwise_fma(wr01, sa2, vka01)); A23 = __builtin_elementwise_fma(A23, w23, __builtin_elementwise_fma(wr23, sa2, vka23));
;                 B01 = __builtin_elementwise_fma(B01, w01, __builtin_elementwise_fma(wr01, sb2, vkb01)); B23 = __builtin_elementwise_fma(B23, w23, __builtin_elementwise_fma(wr23, sb2, vkb23));
;                 f32x2 ya = A01 * r01; ya = __builtin_elementwise_fma(A23, r23, ya);
;                 f32x2 yb = B01 * r01; yb = __builtin_elementwise_fma(B23, r23, yb);
;                 Y[s * 512] = ya[0] + ya[1]; Y[s * 512 + 64] = yb[0] + yb[1];
;                 __builtin_amdgcn_sched_barrier(0);
;                 cw = nw; cm = nm; cwr = nwr; ck = nk; cr = nr; cva = nva; cvb = nvb;
;             }
	v_pk_mul_f32 v[46:47], v[12:13], v[28:29] op_sel_hi:[1,0]
	ds_read_b128 v[68:71], v21 offset:12928
	v_pk_mul_f32 v[48:49], v[12:13], v[80:81] op_sel_hi:[1,0]
	ds_read_b128 v[76:79], v21 offset:13440
	v_pk_fma_f32 v[46:47], v[14:15], v[28:29], v[46:47] op_sel:[0,1,0]
	ds_read_b32 v84, v22 offset:13952
	v_pk_fma_f32 v[48:49], v[14:15], v[80:81], v[48:49] op_sel:[0,1,0]
	ds_read_b32 v85, v22 offset:13968
	v_pk_fma_f32 v[46:47], v[16:17], v[30:31], v[46:47] op_sel_hi:[1,0,1]
	ds_read_b128 v[64:67], v21 offset:12672
	v_pk_fma_f32 v[48:49], v[16:17], v[82:83], v[48:49] op_sel_hi:[1,0,1]
	ds_read_b128 v[72:75], v21 offset:13184
	v_pk_fma_f32 v[46:47], v[18:19], v[30:31], v[46:47] op_sel:[0,1,0]
	v_pk_fma_f32 v[48:49], v[18:19], v[82:83], v[48:49] op_sel:[0,1,0]
	v_pk_mul_f32 v[248:249], v[36:37], v[44:45] op_sel_hi:[0,1]
	v_pk_mul_f32 v[250:251], v[36:37], v[44:45] op_sel:[1,0]
	v_add_f32_dpp v46, v46, v46 quad_perm:[1,0,3,2] row_mask:0xf bank_mask:0xf bound_ctrl:1
	v_add_f32_dpp v47, v47, v47 quad_perm:[1,0,3,2] row_mask:0xf bank_mask:0xf bound_ctrl:1
	ds_write2st64_b32 v20, v48, v49 offset0:56 offset1:57
	v_add_f32_dpp v46, v46, v46 quad_perm:[2,3,0,1] row_mask:0xf bank_mask:0xf bound_ctrl:1
	v_add_f32_dpp v47, v47, v47 quad_perm:[2,3,0,1] row_mask:0xf bank_mask:0xf bound_ctrl:1
	ds_read_b128 v[80:83], v21 offset:13696
	v_add_f32_dpp v46, v46, v46 row_half_mirror row_mask:0xf bank_mask:0xf bound_ctrl:1
	v_add_f32_dpp v47, v47, v47 row_half_mirror row_mask:0xf bank_mask:0xf bound_ctrl:1
	v_pk_mul_f32 v[252:253], v[38:39], v[44:45] op_sel_hi:[0,1]
	v_add_f32_dpp v46, v46, v46 row_mirror row_mask:0xf bank_mask:0xf bound_ctrl:1
	v_add_f32_dpp v47, v47, v47 row_mirror row_mask:0xf bank_mask:0xf bound_ctrl:1
	v_pk_mul_f32 v[254:255], v[38:39], v[44:45] op_sel:[1,0]
	v_pk_fma_f32 v[248:249], v[12:13], v[24:25], v[248:249] op_sel_hi:[1,0,1]
	v_pk_fma_f32 v[250:251], v[14:15], v[24:25], v[250:251] op_sel:[0,1,0]
	v_pk_fma_f32 v[252:253], v[16:17], v[26:27], v[252:253] op_sel_hi:[1,0,1]
	v_pk_fma_f32 v[254:255], v[18:19], v[26:27], v[254:255] op_sel:[0,1,0]
	v_pk_fma_f32 v[12:13], v[32:33], v[46:47], v[248:249] op_sel_hi:[0,1,1]
	v_pk_fma_f32 v[14:15], v[32:33], v[46:47], v[250:251] op_sel:[1,0,0]
	v_pk_fma_f32 v[16:17], v[34:35], v[46:47], v[252:253] op_sel_hi:[0,1,1]
	v_pk_fma_f32 v[18:19], v[34:35], v[46:47], v[254:255] op_sel:[1,0,0]
	s_waitcnt lgkmcnt(1)
	v_pk_mul_f32 v[46:47], v[12:13], v[68:69] op_sel_hi:[1,0]
	ds_read_b128 v[28:31], v21 offset:14336
	v_pk_mul_f32 v[48:49], v[12:13], v[40:41] op_sel_hi:[1,0]
	ds_read_b128 v[36:39], v21 offset:14848
	v_pk_fma_f32 v[46:47], v[14:15], v[68:69], v[46:47] op_sel:[0,1,0]
	ds_read_b32 v44, v22 offset:15360
	v_pk_fma_f32 v[48:49], v[14:15], v[40:41], v[48:49] op_sel:[0,1,0]
	ds_read_b32 v45, v22 offset:15376
	v_pk_fma_f32 v[46:47], v[16:17], v[70:71], v[46:47] op_sel_hi:[1,0,1]
	ds_read_b128 v[24:27], v21 offset:14080
	v_pk_fma_f32 v[48:49], v[16:17], v[42:43], v[48:49] op_sel_hi:[1,0,1]
	ds_read_b128 v[32:35], v21 offset:14592
	v_pk_fma_f32 v[46:47], v[18:19], v[70:71], v[46:47] op_sel:[0,1,0]
	v_pk_fma_f32 v[48:49], v[18:19], v[42:43], v[48:49] op_sel:[0,1,0]
	v_pk_mul_f32 v[248:249], v[76:77], v[84:85] op_sel_hi:[0,1]
	v_pk_mul_f32 v[250:251], v[76:77], v[84:85] op_sel:[1,0]
	v_add_f32_dpp v46, v46, v46 quad_perm:[1,0,3,2] row_mask:0xf bank_mask:0xf bound_ctrl:1
	v_add_f32_dpp v47, v47, v47 quad_perm:[1,0,3,2] row_mask:0xf bank_mask:0xf bound_ctrl:1
	ds_write2st64_b32 v20, v48, v49 offset0:64 offset1:65
	v_add_f32_dpp v46, v46, v46 quad_perm:[2,3,0,1] row_mask:0xf bank_mask:0xf bound_ctrl:1
	v_add_f32_dpp v47, v47, v47 quad_perm:[2,3,0,1] row_mask:0xf bank_mask:0xf bound_ctrl:1
	ds_read_b128 v[40:43], v21 offset:15104
	v_add_f32_dpp v46, v46, v46 row_half_mirror row_mask:0xf bank_mask:0xf bound_ctrl:1
	v_add_f32_dpp v47, v47, v47 row_half_mirror row_mask:0xf bank_mask:0xf bound_ctrl:1
	v_pk_mul_f32 v[252:253], v[78:79], v[84:85] op_sel_hi:[0,1]
	v_add_f32_dpp v46, v46, v46 row_mirror row_mask:0xf bank_mask:0xf bound_ctrl:1
	v_add_f32_dpp v47, v47, v47 row_mirror row_mask:0xf bank_mask:0xf bound_ctrl:1
	v_pk_mul_f32 v[254:255], v[78:79], v[84:85] op_sel:[1,0]
	v_pk_fma_f32 v[248:249], v[12:13], v[64:65], v[248:249] op_sel_hi:[1,0,1]
	v_pk_fma_f32 v[250:251], v[14:15], v[64:65], v[250:251] op_sel:[0,1,0]
	v_pk_fma_f32 v[252:253], v[16:17], v[66:67], v[252:253] op_sel_hi:[1,0,1]
	v_pk_fma_f32 v[254:255], v[18:19], v[66:67], v[254:255] op_sel:[0,1,0]
	v_pk_fma_f32 v[12:13], v[72:73], v[46:47], v[248:249] op_sel_hi:[0,1,1]
	v_pk_fma_f32 v[14:15], v[72:73], v[46:47], v[250:251] op_sel:[1,0,0]
	v_pk_fma_f32 v[16:17], v[74:75], v[46:47], v[252:253] op_sel_hi:[0,1,1]
	v_pk_fma_f32 v[18:19], v[74:75], v[46:47], v[254:255] op_sel:[1,0,0]
	s_waitcnt lgkmcnt(1)
; template <int CTRL> __device__ __forceinline__ float dppf(float x) { return __builtin_bit_cast(float, __builtin_amdgcn_update_dpp(0, __builtin_bit_cast(int, x), CTRL, 0xf, 0xf, true)); }
; __device__ __forceinline__ void scan_item(LAS unsigned char* lds, const ScanPtrs& P, bf16* YC, int item, unsigned* half_cnt, unsigned half_expect) {
;     ...
;             for (int s = 0; s < SC_TC; ++s) {
;                 if (s + 1 < SC_TC) SC_RD(s + 1, nw, nm, nwr, nk, nr, nva, nvb);
;                 __builtin_amdgcn_sched_barrier(0);
;                 const f32x2 m01 = {cm[0], cm[1]}, m23 = {cm[2], cm[3]}, w01 = {cw[0], cw[1]}, w23 = {cw[2], cw[3]}, wr01 = {cwr[0], cwr[1]}, wr23 = {cwr[2], cwr[3]},
;                             k01 = {ck[0], ck[1]}, k23 = {ck[2], ck[3]}, r01 = {cr[0], cr[1]}, r23 = {cr[2], cr[3]};
;                 f32x2 qa = A01 * m01; qa = __builtin_elementwise_fma(A23, m23, qa);
;                 f32x2 qb = B01 * m01; qb = __builtin_elementwise_fma(B23, m23, qb);
;                 float da = qa[0] + qa[1], db = qb[0] + qb[1];
;                 const f32x2 vka01 = k01 * cva, vka23 = k23 * cva, vkb01 = k01 * cvb, vkb23 = k23 * cvb;
;                 da += dppf<0xB1>(da);  db += dppf<0xB1>(db);
;                 da += dppf<0x4E>(da);  db += dppf<0x4E>(db);
;                 da += dppf<0x141>(da); db += dppf<0x141>(db);
;                 da += dppf<0x140>(da); db += dppf<0x140>(db);
;                 const f32x2 sa2 = {da, da}, sb2 = {db, db};
;                 A01 = __builtin_elementwise_fma(A01, w01, __builtin_elementwise_fma(wr01, sa2, vka01)); A23 = __builtin_elementwise_fma(A23, w23, __builtin_elementwise_fma(wr23, sa2, vka23));
;                 B01 = __builtin_elementwise_fma(B01, w01, __builtin_elementwise_fma(wr01, sb2, vkb01)); B23 = __builtin_elementwise_fma(B23, w23, __builtin_elementwise_fma(wr23, sb2, vkb23));
;                 f32x2 ya = A01 * r01; ya = __builtin_elementwise_fma(A23, r23, ya);
;                 f32x2 yb = B01 * r01; yb = __builtin_elementwise_fma(B23, r23, yb);
;                 Y[s * 512] = ya[0] + ya[1]; Y[s * 512 + 64] = yb[0] + yb[1];
;                 __builtin_amdgcn_sched_barrier(0);
;                 cw = nw; cm = nm; cwr = nwr; ck = nk; cr = nr; cva = nva; cvb = nvb;
;             }
	v_pk_mul_f32 v[46:47], v[12:13], v[28:29] op_sel_hi:[1,0]
	ds_read_b128 v[68:71], v21 offset:15744
	v_pk_mul_f32 v[48:49], v[12:13], v[80:81] op_sel_hi:[1,0]
	ds_read_b128 v[76:79], v21 offset:16256
	v_pk_fma_f32 v[46:47], v[14:15], v[28:29], v[46:47] op_sel:[0,1,0]
	ds_read_b32 v84, v22 offset:16768
	v_pk_fma_f32 v[48:49], v[14:15], v[80:81], v[48:49] op_sel:[0,1,0]
	ds_read_b32 v85, v22 offset:16784
	v_pk_fma_f32 v[46:47], v[16:17], v[30:31], v[46:47] op_sel_hi:[1,0,1]
	ds_read_b128 v[64:67], v21 offset:15488
	v_pk_fma_f32 v[48:49], v[16:17], v[82:83], v[48:49] op_sel_hi:[1,0,1]
	ds_read_b128 v[72:75], v21 offset:16000
	v_pk_fma_f32 v[46:47], v[18:19], v[30:31], v[46:47] op_sel:[0,1,0]
	v_pk_fma_f32 v[48:49], v[18:19], v[82:83], v[48:49] op_sel:[0,1,0]
	v_pk_mul_f32 v[248:249], v[36:37], v[44:45] op_sel_hi:[0,1]
	v_pk_mul_f32 v[250:251], v[36:37], v[44:45] op_sel:[1,0]
	v_add_f32_dpp v46, v46, v46 quad_perm:[1,0,3,2] row_mask:0xf bank_mask:0xf bound_ctrl:1
	v_add_f32_dpp v47, v47, v47 quad_perm:[1,0,3,2] row_mask:0xf bank_mask:0xf bound_ctrl:1
	ds_write2st64_b32 v20, v48, v49 offset0:72 offset1:73
	v_add_f32_dpp v46, v46, v46 quad_perm:[2,3,0,1] row_mask:0xf bank_mask:0xf bound_ctrl:1
	v_add_f32_dpp v47, v47, v47 quad_perm:[2,3,0,1] row_mask:0xf bank_mask:0xf bound_ctrl:1
	ds_read_b128 v[80:83], v21 offset:16512
	v_add_f32_dpp v46, v46, v46 row_half_mirror row_mask:0xf bank_mask:0xf bound_ctrl:1
	v_add_f32_dpp v47, v47, v47 row_half_mirror row_mask:0xf bank_mask:0xf bound_ctrl:1
	v_pk_mul_f32 v[252:253], v[38:39], v[44:45] op_sel_hi:[0,1]
	v_add_f32_dpp v46, v46, v46 row_mirror row_mask:0xf bank_mask:0xf bound_ctrl:1
	v_add_f32_dpp v47, v47, v47 row_mirror row_mask:0xf bank_mask:0xf bound_ctrl:1
	v_pk_mul_f32 v[254:255], v[38:39], v[44:45] op_sel:[1,0]
	v_pk_fma_f32 v[248:249], v[12:13], v[24:25], v[248:249] op_sel_hi:[1,0,1]
	v_pk_fma_f32 v[250:251], v[14:15], v[24:25], v[250:251] op_sel:[0,1,0]
	v_pk_fma_f32 v[252:253], v[16:17], v[26:27], v[252:253] op_sel_hi:[1,0,1]
	v_pk_fma_f32 v[254:255], v[18:19], v[26:27], v[254:255] op_sel:[0,1,0]
	v_pk_fma_f32 v[12:13], v[32:33], v[46:47], v[248:249] op_sel_hi:[0,1,1]
	v_pk_fma_f32 v[14:15], v[32:33], v[46:47], v[250:251] op_sel:[1,0,0]
	v_pk_fma_f32 v[16:17], v[34:35], v[46:47], v[252:253] op_sel_hi:[0,1,1]
	v_pk_fma_f32 v[18:19], v[34:35], v[46:47], v[254:255] op_sel:[1,0,0]
	s_waitcnt lgkmcnt(1)
	v_pk_mul_f32 v[46:47], v[12:13], v[68:69] op_sel_hi:[1,0]
	ds_read_b128 v[28:31], v21 offset:17152
	v_pk_mul_f32 v[48:49], v[12:13], v[40:41] op_sel_hi:[1,0]
	ds_read_b128 v[36:39], v21 offset:17664
	v_pk_fma_f32 v[46:47], v[14:15], v[68:69], v[46:47] op_sel:[0,1,0]
	ds_read_b32 v44, v22 offset:18176
	v_pk_fma_f32 v[48:49], v[14:15], v[40:41], v[48:49] op_sel:[0,1,0]
	ds_read_b32 v45, v22 offset:18192
	v_pk_fma_f32 v[46:47], v[16:17], v[70:71], v[46:47] op_sel_hi:[1,0,1]
	ds_read_b128 v[24:27], v21 offset:16896
	v_pk_fma_f32 v[48:49], v[16:17], v[42:43], v[48:49] op_sel_hi:[1,0,1]
	ds_read_b128 v[32:35], v21 offset:17408
	v_pk_fma_f32 v[46:47], v[18:19], v[70:71], v[46:47] op_sel:[0,1,0]
	v_pk_fma_f32 v[48:49], v[18:19], v[42:43], v[48:49] op_sel:[0,1,0]
	v_pk_mul_f32 v[248:249], v[76:77], v[84:85] op_sel_hi:[0,1]
	v_pk_mul_f32 v[250:251], v[76:77], v[84:85] op_sel:[1,0]
	v_add_f32_dpp v46, v46, v46 quad_perm:[1,0,3,2] row_mask:0xf bank_mask:0xf bound_ctrl:1
	v_add_f32_dpp v47, v47, v47 quad_perm:[1,0,3,2] row_mask:0xf bank_mask:0xf bound_ctrl:1
	ds_write2st64_b32 v20, v48, v49 offset0:80 offset1:81
	v_add_f32_dpp v46, v46, v46 quad_perm:[2,3,0,1] row_mask:0xf bank_mask:0xf bound_ctrl:1
	v_add_f32_dpp v47, v47, v47 quad_perm:[2,3,0,1] row_mask:0xf bank_mask:0xf bound_ctrl:1
	ds_read_b128 v[40:43], v21 offset:17920
	v_add_f32_dpp v46, v46, v46 row_half_mirror row_mask:0xf bank_mask:0xf bound_ctrl:1
	v_add_f32_dpp v47, v47, v47 row_half_mirror row_mask:0xf bank_mask:0xf bound_ctrl:1
	v_pk_mul_f32 v[252:253], v[78:79], v[84:85] op_sel_hi:[0,1]
	v_add_f32_dpp v46, v46, v46 row_mirror row_mask:0xf bank_mask:0xf bound_ctrl:1
	v_add_f32_dpp v47, v47, v47 row_mirror row_mask:0xf bank_mask:0xf bound_ctrl:1
	v_pk_mul_f32 v[254:255], v[78:79], v[84:85] op_sel:[1,0]
	v_pk_fma_f32 v[248:249], v[12:13], v[64:65], v[248:249] op_sel_hi:[1,0,1]
	v_pk_fma_f32 v[250:251], v[14:15], v[64:65], v[250:251] op_sel:[0,1,0]
	v_pk_fma_f32 v[252:253], v[16:17], v[66:67], v[252:253] op_sel_hi:[1,0,1]
	v_pk_fma_f32 v[254:255], v[18:19], v[66:67], v[254:255] op_sel:[0,1,0]
	v_pk_fma_f32 v[12:13], v[72:73], v[46:47], v[248:249] op_sel_hi:[0,1,1]
	v_pk_fma_f32 v[14:15], v[72:73], v[46:47], v[250:251] op_sel:[1,0,0]
	v_pk_fma_f32 v[16:17], v[74:75], v[46:47], v[252:253] op_sel_hi:[0,1,1]
	v_pk_fma_f32 v[18:19], v[74:75], v[46:47], v[254:255] op_sel:[1,0,0]
	s_waitcnt lgkmcnt(1)
; template <int CTRL> __device__ __forceinline__ float dppf(float x) { return __builtin_bit_cast(float, __builtin_amdgcn_update_dpp(0, __builtin_bit_cast(int, x), CTRL, 0xf, 0xf, true)); }
; __device__ __forceinline__ void scan_item(LAS unsigned char* lds, const ScanPtrs& P, bf16* YC, int item, unsigned* half_cnt, unsigned half_expect) {
;     ...
;             for (int s = 0; s < SC_TC; ++s) {
;                 if (s + 1 < SC_TC) SC_RD(s + 1, nw, nm, nwr, nk, nr, nva, nvb);
;                 __builtin_amdgcn_sched_barrier(0);
;                 const f32x2 m01 = {cm[0], cm[1]}, m23 = {cm[2], cm[3]}, w01 = {cw[0], cw[1]}, w23 = {cw[2], cw[3]}, wr01 = {cwr[0], cwr[1]}, wr23 = {cwr[2], cwr[3]},
;                             k01 = {ck[0], ck[1]}, k23 = {ck[2], ck[3]}, r01 = {cr[0], cr[1]}, r23 = {cr[2], cr[3]};
;                 f32x2 qa = A01 * m01; qa = __builtin_elementwise_fma(A23, m23, qa);
;                 f32x2 qb = B01 * m01; qb = __builtin_elementwise_fma(B23, m23, qb);
;                 float da = qa[0] + qa[1], db = qb[0] + qb[1];
;                 const f32x2 vka01 = k01 * cva, vka23 = k23 * cva, vkb01 = k01 * cvb, vkb23 = k23 * cvb;
;                 da += dppf<0xB1>(da);  db += dppf<0xB1>(db);
;                 da += dppf<0x4E>(da);  db += dppf<0x4E>(db);
;                 da += dppf<0x141>(da); db += dppf<0x141>(db);
;                 da += dppf<0x140>(da); db += dppf<0x140>(db);
;                 const f32x2 sa2 = {da, da}, sb2 = {db, db};
;                 A01 = __builtin_elementwise_fma(A01, w01, __builtin_elementwise_fma(wr01, sa2, vka01)); A23 = __builtin_elementwise_fma(A23, w23, __builtin_elementwise_fma(wr23, sa2, vka23));
;                 B01 = __builtin_elementwise_fma(B01, w01, __builtin_elementwise_fma(wr01, sb2, vkb01)); B23 = __builtin_elementwise_fma(B23, w23, __builtin_elementwise_fma(wr23, sb2, vkb23));
;                 f32x2 ya = A01 * r01; ya = __builtin_elementwise_fma(A23, r23, ya);
;                 f32x2 yb = B01 * r01; yb = __builtin_elementwise_fma(B23, r23, yb);
;                 Y[s * 512] = ya[0] + ya[1]; Y[s * 512 + 64] = yb[0] + yb[1];
;                 __builtin_amdgcn_sched_barrier(0);
;                 cw = nw; cm = nm; cwr = nwr; ck = nk; cr = nr; cva = nva; cvb = nvb;
;             }
	v_pk_mul_f32 v[46:47], v[12:13], v[28:29] op_sel_hi:[1,0]
	ds_read_b128 v[68:71], v21 offset:18560
	v_pk_mul_f32 v[48:49], v[12:13], v[80:81] op_sel_hi:[1,0]
	ds_read_b128 v[76:79], v21 offset:19072
	v_pk_fma_f32 v[46:47], v[14:15], v[28:29], v[46:47] op_sel:[0,1,0]
	ds_read_b32 v84, v22 offset:19584
	v_pk_fma_f32 v[48:49], v[14:15], v[80:81], v[48:49] op_sel:[0,1,0]
	ds_read_b32 v85, v22 offset:19600
	v_pk_fma_f32 v[46:47], v[16:17], v[30:31], v[46:47] op_sel_hi:[1,0,1]
	ds_read_b128 v[64:67], v21 offset:18304
	v_pk_fma_f32 v[48:49], v[16:17], v[82:83], v[48:49] op_sel_hi:[1,0,1]
	ds_read_b128 v[72:75], v21 offset:18816
	v_pk_fma_f32 v[46:47], v[18:19], v[30:31], v[46:47] op_sel:[0,1,0]
	v_pk_fma_f32 v[48:49], v[18:19], v[82:83], v[48:49] op_sel:[0,1,0]
	v_pk_mul_f32 v[248:249], v[36:37], v[44:45] op_sel_hi:[0,1]
	v_pk_mul_f32 v[250:251], v[36:37], v[44:45] op_sel:[1,0]
	v_add_f32_dpp v46, v46, v46 quad_perm:[1,0,3,2] row_mask:0xf bank_mask:0xf bound_ctrl:1
	v_add_f32_dpp v47, v47, v47 quad_perm:[1,0,3,2] row_mask:0xf bank_mask:0xf bound_ctrl:1
	ds_write2st64_b32 v20, v48, v49 offset0:88 offset1:89
	v_add_f32_dpp v46, v46, v46 quad_perm:[2,3,0,1] row_mask:0xf bank_mask:0xf bound_ctrl:1
	v_add_f32_dpp v47, v47, v47 quad_perm:[2,3,0,1] row_mask:0xf bank_mask:0xf bound_ctrl:1
	ds_read_b128 v[80:83], v21 offset:19328
	v_add_f32_dpp v46, v46, v46 row_half_mirror row_mask:0xf bank_mask:0xf bound_ctrl:1
	v_add_f32_dpp v47, v47, v47 row_half_mirror row_mask:0xf bank_mask:0xf bound_ctrl:1
	v_pk_mul_f32 v[252:253], v[38:39], v[44:45] op_sel_hi:[0,1]
	v_add_f32_dpp v46, v46, v46 row_mirror row_mask:0xf bank_mask:0xf bound_ctrl:1
	v_add_f32_dpp v47, v47, v47 row_mirror row_mask:0xf bank_mask:0xf bound_ctrl:1
	v_pk_mul_f32 v[254:255], v[38:39], v[44:45] op_sel:[1,0]
	v_pk_fma_f32 v[248:249], v[12:13], v[24:25], v[248:249] op_sel_hi:[1,0,1]
	v_pk_fma_f32 v[250:251], v[14:15], v[24:25], v[250:251] op_sel:[0,1,0]
	v_pk_fma_f32 v[252:253], v[16:17], v[26:27], v[252:253] op_sel_hi:[1,0,1]
	v_pk_fma_f32 v[254:255], v[18:19], v[26:27], v[254:255] op_sel:[0,1,0]
	v_pk_fma_f32 v[12:13], v[32:33], v[46:47], v[248:249] op_sel_hi:[0,1,1]
	v_pk_fma_f32 v[14:15], v[32:33], v[46:47], v[250:251] op_sel:[1,0,0]
	v_pk_fma_f32 v[16:17], v[34:35], v[46:47], v[252:253] op_sel_hi:[0,1,1]
	v_pk_fma_f32 v[18:19], v[34:35], v[46:47], v[254:255] op_sel:[1,0,0]
	s_waitcnt lgkmcnt(1)
	v_pk_mul_f32 v[46:47], v[12:13], v[68:69] op_sel_hi:[1,0]
	ds_read_b128 v[28:31], v21 offset:19968
	v_pk_mul_f32 v[48:49], v[12:13], v[40:41] op_sel_hi:[1,0]
	ds_read_b128 v[36:39], v21 offset:20480
	v_pk_fma_f32 v[46:47], v[14:15], v[68:69], v[46:47] op_sel:[0,1,0]
	ds_read_b32 v44, v22 offset:20992
	v_pk_fma_f32 v[48:49], v[14:15], v[40:41], v[48:49] op_sel:[0,1,0]
	ds_read_b32 v45, v22 offset:21008
	v_pk_fma_f32 v[46:47], v[16:17], v[70:71], v[46:47] op_sel_hi:[1,0,1]
	ds_read_b128 v[24:27], v21 offset:19712
	v_pk_fma_f32 v[48:49], v[16:17], v[42:43], v[48:49] op_sel_hi:[1,0,1]
	ds_read_b128 v[32:35], v21 offset:20224
	v_pk_fma_f32 v[46:47], v[18:19], v[70:71], v[46:47] op_sel:[0,1,0]
	v_pk_fma_f32 v[48:49], v[18:19], v[42:43], v[48:49] op_sel:[0,1,0]
	v_pk_mul_f32 v[248:249], v[76:77], v[84:85] op_sel_hi:[0,1]
	v_pk_mul_f32 v[250:251], v[76:77], v[84:85] op_sel:[1,0]
	v_add_f32_dpp v46, v46, v46 quad_perm:[1,0,3,2] row_mask:0xf bank_mask:0xf bound_ctrl:1
	v_add_f32_dpp v47, v47, v47 quad_perm:[1,0,3,2] row_mask:0xf bank_mask:0xf bound_ctrl:1
	ds_write2st64_b32 v20, v48, v49 offset0:96 offset1:97
	v_add_f32_dpp v46, v46, v46 quad_perm:[2,3,0,1] row_mask:0xf bank_mask:0xf bound_ctrl:1
	v_add_f32_dpp v47, v47, v47 quad_perm:[2,3,0,1] row_mask:0xf bank_mask:0xf bound_ctrl:1
	ds_read_b128 v[40:43], v21 offset:20736
	v_add_f32_dpp v46, v46, v46 row_half_mirror row_mask:0xf bank_mask:0xf bound_ctrl:1
	v_add_f32_dpp v47, v47, v47 row_half_mirror row_mask:0xf bank_mask:0xf bound_ctrl:1
	v_pk_mul_f32 v[252:253], v[78:79], v[84:85] op_sel_hi:[0,1]
	v_add_f32_dpp v46, v46, v46 row_mirror row_mask:0xf bank_mask:0xf bound_ctrl:1
	v_add_f32_dpp v47, v47, v47 row_mirror row_mask:0xf bank_mask:0xf bound_ctrl:1
	v_pk_mul_f32 v[254:255], v[78:79], v[84:85] op_sel:[1,0]
	v_pk_fma_f32 v[248:249], v[12:13], v[64:65], v[248:249] op_sel_hi:[1,0,1]
	v_pk_fma_f32 v[250:251], v[14:15], v[64:65], v[250:251] op_sel:[0,1,0]
	v_pk_fma_f32 v[252:253], v[16:17], v[66:67], v[252:253] op_sel_hi:[1,0,1]
	v_pk_fma_f32 v[254:255], v[18:19], v[66:67], v[254:255] op_sel:[0,1,0]
	v_pk_fma_f32 v[12:13], v[72:73], v[46:47], v[248:249] op_sel_hi:[0,1,1]
	v_pk_fma_f32 v[14:15], v[72:73], v[46:47], v[250:251] op_sel:[1,0,0]
	v_pk_fma_f32 v[16:17], v[74:75], v[46:47], v[252:253] op_sel_hi:[0,1,1]
	v_pk_fma_f32 v[18:19], v[74:75], v[46:47], v[254:255] op_sel:[1,0,0]
	s_waitcnt lgkmcnt(1)
; template <int CTRL> __device__ __forceinline__ float dppf(float x) { return __builtin_bit_cast(float, __builtin_amdgcn_update_dpp(0, __builtin_bit_cast(int, x), CTRL, 0xf, 0xf, true)); }
; __device__ __forceinline__ void scan_item(LAS unsigned char* lds, const ScanPtrs& P, bf16* YC, int item, unsigned* half_cnt, unsigned half_expect) {
;     ...
;             for (int s = 0; s < SC_TC; ++s) {
;                 if (s + 1 < SC_TC) SC_RD(s + 1, nw, nm, nwr, nk, nr, nva, nvb);
;                 __builtin_amdgcn_sched_barrier(0);
;                 const f32x2 m01 = {cm[0], cm[1]}, m23 = {cm[2], cm[3]}, w01 = {cw[0], cw[1]}, w23 = {cw[2], cw[3]}, wr01 = {cwr[0], cwr[1]}, wr23 = {cwr[2], cwr[3]},
;                             k01 = {ck[0], ck[1]}, k23 = {ck[2], ck[3]}, r01 = {cr[0], cr[1]}, r23 = {cr[2], cr[3]};
;                 f32x2 qa = A01 * m01; qa = __builtin_elementwise_fma(A23, m23, qa);
;                 f32x2 qb = B01 * m01; qb = __builtin_elementwise_fma(B23, m23, qb);
;                 float da = qa[0] + qa[1], db = qb[0] + qb[1];
;                 const f32x2 vka01 = k01 * cva, vka23 = k23 * cva, vkb01 = k01 * cvb, vkb23 = k23 * cvb;
;                 da += dppf<0xB1>(da);  db += dppf<0xB1>(db);
;                 da += dppf<0x4E>(da);  db += dppf<0x4E>(db);
;                 da += dppf<0x141>(da); db += dppf<0x141>(db);
;                 da += dppf<0x140>(da); db += dppf<0x140>(db);
;                 const f32x2 sa2 = {da, da}, sb2 = {db, db};
;                 A01 = __builtin_elementwise_fma(A01, w01, __builtin_elementwise_fma(wr01, sa2, vka01)); A23 = __builtin_elementwise_fma(A23, w23, __builtin_elementwise_fma(wr23, sa2, vka23));
;                 B01 = __builtin_elementwise_fma(B01, w01, __builtin_elementwise_fma(wr01, sb2, vkb01)); B23 = __builtin_elementwise_fma(B23, w23, __builtin_elementwise_fma(wr23, sb2, vkb23));
;                 f32x2 ya = A01 * r01; ya = __builtin_elementwise_fma(A23, r23, ya);
;                 f32x2 yb = B01 * r01; yb = __builtin_elementwise_fma(B23, r23, yb);
;                 Y[s * 512] = ya[0] + ya[1]; Y[s * 512 + 64] = yb[0] + yb[1];
;                 __builtin_amdgcn_sched_barrier(0);
;                 cw = nw; cm = nm; cwr = nwr; ck = nk; cr = nr; cva = nva; cvb = nvb;
;             }
;     ...
;             __syncthreads();
;         }
	v_pk_mul_f32 v[46:47], v[12:13], v[28:29] op_sel_hi:[1,0]
	ds_read_b128 v[68:71], v21 offset:21376
	v_pk_mul_f32 v[48:49], v[12:13], v[80:81] op_sel_hi:[1,0]
	ds_read_b128 v[76:79], v21 offset:21888
	v_pk_fma_f32 v[46:47], v[14:15], v[28:29], v[46:47] op_sel:[0,1,0]
	ds_read_b32 v84, v22 offset:22400
	v_pk_fma_f32 v[48:49], v[14:15], v[80:81], v[48:49] op_sel:[0,1,0]
	ds_read_b32 v85, v22 offset:22416
	v_pk_fma_f32 v[46:47], v[16:17], v[30:31], v[46:47] op_sel_hi:[1,0,1]
	ds_read_b128 v[64:67], v21 offset:21120
	v_pk_fma_f32 v[48:49], v[16:17], v[82:83], v[48:49] op_sel_hi:[1,0,1]
	ds_read_b128 v[72:75], v21 offset:21632
	v_pk_fma_f32 v[46:47], v[18:19], v[30:31], v[46:47] op_sel:[0,1,0]
	v_pk_fma_f32 v[48:49], v[18:19], v[82:83], v[48:49] op_sel:[0,1,0]
	v_pk_mul_f32 v[248:249], v[36:37], v[44:45] op_sel_hi:[0,1]
	v_pk_mul_f32 v[250:251], v[36:37], v[44:45] op_sel:[1,0]
	v_add_f32_dpp v46, v46, v46 quad_perm:[1,0,3,2] row_mask:0xf bank_mask:0xf bound_ctrl:1
	v_add_f32_dpp v47, v47, v47 quad_perm:[1,0,3,2] row_mask:0xf bank_mask:0xf bound_ctrl:1
	ds_write2st64_b32 v20, v48, v49 offset0:104 offset1:105
	v_add_f32_dpp v46, v46, v46 quad_perm:[2,3,0,1] row_mask:0xf bank_mask:0xf bound_ctrl:1
	v_add_f32_dpp v47, v47, v47 quad_perm:[2,3,0,1] row_mask:0xf bank_mask:0xf bound_ctrl:1
	ds_read_b128 v[80:83], v21 offset:22144
	v_add_f32_dpp v46, v46, v46 row_half_mirror row_mask:0xf bank_mask:0xf bound_ctrl:1
	v_add_f32_dpp v47, v47, v47 row_half_mirror row_mask:0xf bank_mask:0xf bound_ctrl:1
	v_pk_mul_f32 v[252:253], v[38:39], v[44:45] op_sel_hi:[0,1]
	v_add_f32_dpp v46, v46, v46 row_mirror row_mask:0xf bank_mask:0xf bound_ctrl:1
	v_add_f32_dpp v47, v47, v47 row_mirror row_mask:0xf bank_mask:0xf bound_ctrl:1
	v_pk_mul_f32 v[254:255], v[38:39], v[44:45] op_sel:[1,0]
	v_pk_fma_f32 v[248:249], v[12:13], v[24:25], v[248:249] op_sel_hi:[1,0,1]
	v_pk_fma_f32 v[250:251], v[14:15], v[24:25], v[250:251] op_sel:[0,1,0]
	v_pk_fma_f32 v[252:253], v[16:17], v[26:27], v[252:253] op_sel_hi:[1,0,1]
	v_pk_fma_f32 v[254:255], v[18:19], v[26:27], v[254:255] op_sel:[0,1,0]
	v_pk_fma_f32 v[12:13], v[32:33], v[46:47], v[248:249] op_sel_hi:[0,1,1]
	v_pk_fma_f32 v[14:15], v[32:33], v[46:47], v[250:251] op_sel:[1,0,0]
	v_pk_fma_f32 v[16:17], v[34:35], v[46:47], v[252:253] op_sel_hi:[0,1,1]
	v_pk_fma_f32 v[18:19], v[34:35], v[46:47], v[254:255] op_sel:[1,0,0]
	s_waitcnt lgkmcnt(0)
	v_pk_mul_f32 v[46:47], v[12:13], v[68:69] op_sel_hi:[1,0]
	v_pk_mul_f32 v[48:49], v[12:13], v[40:41] op_sel_hi:[1,0]
	v_pk_fma_f32 v[46:47], v[14:15], v[68:69], v[46:47] op_sel:[0,1,0]
	v_pk_fma_f32 v[48:49], v[14:15], v[40:41], v[48:49] op_sel:[0,1,0]
	v_pk_fma_f32 v[46:47], v[16:17], v[70:71], v[46:47] op_sel_hi:[1,0,1]
	v_pk_fma_f32 v[48:49], v[16:17], v[42:43], v[48:49] op_sel_hi:[1,0,1]
	v_pk_fma_f32 v[46:47], v[18:19], v[70:71], v[46:47] op_sel:[0,1,0]
	v_pk_fma_f32 v[48:49], v[18:19], v[42:43], v[48:49] op_sel:[0,1,0]
	v_pk_mul_f32 v[248:249], v[76:77], v[84:85] op_sel_hi:[0,1]
	v_pk_mul_f32 v[250:251], v[76:77], v[84:85] op_sel:[1,0]
	v_add_f32_dpp v46, v46, v46 quad_perm:[1,0,3,2] row_mask:0xf bank_mask:0xf bound_ctrl:1
	v_add_f32_dpp v47, v47, v47 quad_perm:[1,0,3,2] row_mask:0xf bank_mask:0xf bound_ctrl:1
	ds_write2st64_b32 v20, v48, v49 offset0:112 offset1:113
	v_add_f32_dpp v46, v46, v46 quad_perm:[2,3,0,1] row_mask:0xf bank_mask:0xf bound_ctrl:1
	v_add_f32_dpp v47, v47, v47 quad_perm:[2,3,0,1] row_mask:0xf bank_mask:0xf bound_ctrl:1
	v_pk_mul_f32 v[252:253], v[78:79], v[84:85] op_sel_hi:[0,1]
	v_add_f32_dpp v46, v46, v46 row_half_mirror row_mask:0xf bank_mask:0xf bound_ctrl:1
	v_add_f32_dpp v47, v47, v47 row_half_mirror row_mask:0xf bank_mask:0xf bound_ctrl:1
	v_pk_mul_f32 v[254:255], v[78:79], v[84:85] op_sel:[1,0]
	v_add_f32_dpp v46, v46, v46 row_mirror row_mask:0xf bank_mask:0xf bound_ctrl:1
	v_add_f32_dpp v47, v47, v47 row_mirror row_mask:0xf bank_mask:0xf bound_ctrl:1
	v_pk_fma_f32 v[248:249], v[12:13], v[64:65], v[248:249] op_sel_hi:[1,0,1]
	v_pk_fma_f32 v[250:251], v[14:15], v[64:65], v[250:251] op_sel:[0,1,0]
	v_pk_fma_f32 v[252:253], v[16:17], v[66:67], v[252:253] op_sel_hi:[1,0,1]
	v_pk_fma_f32 v[254:255], v[18:19], v[66:67], v[254:255] op_sel:[0,1,0]
	v_pk_fma_f32 v[12:13], v[72:73], v[46:47], v[248:249] op_sel_hi:[0,1,1]
	v_pk_fma_f32 v[14:15], v[72:73], v[46:47], v[250:251] op_sel:[1,0,0]
	v_pk_fma_f32 v[16:17], v[74:75], v[46:47], v[252:253] op_sel_hi:[0,1,1]
	v_pk_fma_f32 v[18:19], v[74:75], v[46:47], v[254:255] op_sel:[1,0,0]
	s_waitcnt lgkmcnt(0)
	s_add_i32 s0, s0, 1
	v_pk_mul_f32 v[48:49], v[12:13], v[80:81] op_sel_hi:[1,0]
	s_and_b32 s2, s0, 1
	v_pk_fma_f32 v[48:49], v[14:15], v[80:81], v[48:49] op_sel:[0,1,0]
	s_mul_i32 s3, s2, 0x5800
	v_pk_fma_f32 v[48:49], v[16:17], v[82:83], v[48:49] op_sel_hi:[1,0,1]
	s_addk_i32 s3, 0x100
	v_pk_fma_f32 v[48:49], v[18:19], v[82:83], v[48:49] op_sel:[0,1,0]
	v_lshl_add_u32 v22, v6, 2, s3
	v_add_u32_e32 v21, s3, v3
	ds_write2st64_b32 v20, v48, v49 offset0:120 offset1:121
	v_lshl_add_u32 v23, s2, 15, v11
	v_add_u32_e32 v20, 0xb000, v23
	s_cmpk_eq_i32 s0, 0x100
	s_waitcnt lgkmcnt(0)
	s_barrier
	s_cbranch_scc0 .LBB0_728
	s_setprio 0
	s_mov_b64 s[2:3], 0

; __global__ void __launch_bounds__(512, 2) mk_fwd(Args args) {
	.amdhsa_kernel _Z6mk_fwd4Args
		.amdhsa_group_segment_fixed_size 256
		.amdhsa_private_segment_fixed_size 0
		.amdhsa_kernarg_size 512
		.amdhsa_user_sgpr_count 2
		.amdhsa_user_sgpr_dispatch_ptr 0
		.amdhsa_user_sgpr_queue_ptr 0
		.amdhsa_user_sgpr_kernarg_segment_ptr 1
		.amdhsa_user_sgpr_dispatch_id 0
		.amdhsa_user_sgpr_kernarg_preload_length 0
		.amdhsa_user_sgpr_kernarg_preload_offset 0
		.amdhsa_user_sgpr_private_segment_size 0
		.amdhsa_uses_dynamic_stack 0
		.amdhsa_enable_private_segment 0
		.amdhsa_system_sgpr_workgroup_id_x 1
		.amdhsa_system_sgpr_workgroup_id_y 0
		.amdhsa_system_sgpr_workgroup_id_z 0
		.amdhsa_system_sgpr_workgroup_info 0
		.amdhsa_system_vgpr_workitem_id 2
		.amdhsa_next_free_vgpr 256
		.amdhsa_next_free_sgpr 98
		.amdhsa_accum_offset 256
		.amdhsa_reserve_vcc 1
		.amdhsa_float_round_mode_32 0
		.amdhsa_float_round_mode_16_64 0
		.amdhsa_float_denorm_mode_32 3
		.amdhsa_float_denorm_mode_16_64 3
		.amdhsa_dx10_clamp 1
		.amdhsa_ieee_mode 1
		.amdhsa_fp16_overflow 0
		.amdhsa_tg_split 0
		.amdhsa_exception_fp_ieee_invalid_op 0
		.amdhsa_exception_fp_denorm_src 0
		.amdhsa_exception_fp_ieee_div_zero 0
		.amdhsa_exception_fp_ieee_overflow 0
		.amdhsa_exception_fp_ieee_underflow 0
		.amdhsa_exception_fp_ieee_inexact 0
		.amdhsa_exception_int_div_zero 0
	.end_amdhsa_kernel

; __global__ void __launch_bounds__(512, 2) mk_fwd(Args args) {
amdhsa.kernels:
  - .agpr_count:     0
    .args:
      - .offset:         0
        .size:           256
        .value_kind:     by_value
      - .offset:         256
        .size:           4
        .value_kind:     hidden_block_count_x
      - .offset:         260
        .size:           4
        .value_kind:     hidden_block_count_y
      - .offset:         264
        .size:           4
        .value_kind:     hidden_block_count_z
      - .offset:         268
        .size:           2
        .value_kind:     hidden_group_size_x
      - .offset:         270
        .size:           2
        .value_kind:     hidden_group_size_y
      - .offset:         272
        .size:           2
        .value_kind:     hidden_group_size_z
      - .offset:         274
        .size:           2
        .value_kind:     hidden_remainder_x
      - .offset:         276
        .size:           2
        .value_kind:     hidden_remainder_y
      - .offset:         278
        .size:           2
        .value_kind:     hidden_remainder_z
      - .offset:         296
        .size:           8
        .value_kind:     hidden_global_offset_x
      - .offset:         304
        .size:           8
        .value_kind:     hidden_global_offset_y
      - .offset:         312
        .size:           8
        .value_kind:     hidden_global_offset_z
      - .offset:         320
        .size:           2
        .value_kind:     hidden_grid_dims
      - .offset:         344
        .size:           8
        .value_kind:     hidden_multigrid_sync_arg
      - .offset:         376
        .size:           4
        .value_kind:     hidden_dynamic_lds_size
    .group_segment_fixed_size: 256
    .kernarg_segment_align: 8
    .kernarg_segment_size: 512
    .language:       OpenCL C
    .language_version:
      - 2
      - 0
    .max_flat_workgroup_size: 512
    .name:           _Z6mk_fwd4Args
    .private_segment_fixed_size: 0
    .sgpr_count:     104
    .sgpr_spill_count: 71
    .symbol:         _Z6mk_fwd4Args.kd
    .uniform_work_group_size: 1
    .uses_dynamic_stack: false
    .vgpr_count:     256
    .vgpr_spill_count: 0
    .wavefront_size: 64
